# first use of each barrier: the per-XCC arrival atomic is issued before the XCC census loads (one round trip less on thread 0's path at the split barrier and at the P2->P3 seam)
# speedup vs baseline: 1.0017x; 1.0017x over previous
; __device__ __forceinline__ unsigned xb_add(unsigned* p, unsigned v) { return __hip_atomic_fetch_add(p, v, __ATOMIC_RELAXED, __HIP_MEMORY_SCOPE_AGENT); }
; __device__ __forceinline__ void xcd_barrier(const XcdBarrier& b) {
;     ...
;         unsigned nloc = b.st[0], nx = b.st[1];
;         if (nloc == 0u) { xcd_barrier_complete(bar, b.x, b.gsize, nloc, nx); b.st[0] = nloc; b.st[1] = nx; }
;         const unsigned old = xb_add(&bar[XB_XSUB(b.x)], 1u);
.LBB0_13:
	s_waitcnt vmcnt(0)
	v_readlane_b32 s80, v250, 11
	v_readlane_b32 s81, v250, 12
	s_waitcnt lgkmcnt(0)
	s_barrier
	s_and_saveexec_b64 s[4:5], s[80:81]
	s_load_dwordx2 s[60:61], s[0:1], 0xa0
	v_readlane_b32 s96, v250, 8
	v_readlane_b32 s97, v250, 9
	s_cbranch_execz .LBB0_65
	s_add_i32 s6, 0, 0x26160
	v_mov_b32_e32 v1, s6
	s_waitcnt vmcnt(0) expcnt(0) lgkmcnt(0)
	s_lshl_b32 s8, s3, 8
	s_add_u32 s8, s96, s8
	s_addc_u32 s9, s97, 0
	v_mov_b32_e32 v19, 0x1000
	v_mov_b32_e32 v20, 1
	global_atomic_add v19, v19, v20, s[8:9] offset:1024 sc0
	ds_read_b32 v3, v1
	s_add_i32 s6, 0, 0x26164
	v_mov_b32_e32 v1, s6
	ds_read_b32 v1, v1
	s_waitcnt lgkmcnt(1)
	v_cmp_ne_u32_e32 vcc, 0, v3
	s_cbranch_vccnz .LBB0_29
	s_add_u32 s6, s60, 0x4200
	s_addc_u32 s7, s61, 0
	s_add_u32 s8, s60, 0x4400
	s_addc_u32 s9, s61, 0
	s_add_u32 s10, s60, 0x4500
	s_addc_u32 s11, s61, 0
	s_add_u32 s12, s60, 0x4600
	s_addc_u32 s13, s61, 0
	s_add_u32 s16, s60, 0x4700
	s_addc_u32 s17, s61, 0
	s_add_u32 s18, s60, 0x4800
	s_addc_u32 s19, s61, 0
	s_add_u32 s20, s60, 0x4900
	s_addc_u32 s21, s61, 0
	s_add_u32 s22, s60, 0x4a00
	s_addc_u32 s23, s61, 0
	s_add_u32 s24, s60, 0x4b00
	s_addc_u32 s25, s61, 0
	s_add_u32 s26, s60, 0x4c00
	s_addc_u32 s27, s61, 0
	s_add_u32 s28, s60, 0x4d00
	s_addc_u32 s29, s61, 0
	s_add_u32 s30, s60, 0x4e00
	s_addc_u32 s31, s61, 0
	s_add_u32 s40, s60, 0x4f00
	s_addc_u32 s41, s61, 0
	s_add_u32 s42, s60, 0x5000
	s_addc_u32 s43, s61, 0
	s_add_u32 s44, s60, 0x5100
	s_addc_u32 s45, s61, 0
	s_add_u32 s62, s60, 0x5200
	s_addc_u32 s63, s61, 0
	s_add_u32 s64, s60, 0x5300
	s_addc_u32 s65, s61, 0
	s_mov_b32 s14, 1
	v_mov_b32_e32 v17, 0
	s_branch .LBB0_17

; __device__ __forceinline__ unsigned xb_add(unsigned* p, unsigned v) { return __hip_atomic_fetch_add(p, v, __ATOMIC_RELAXED, __HIP_MEMORY_SCOPE_AGENT); }
; __device__ __forceinline__ void xcd_barrier(const XcdBarrier& b) {
;     ...
;         const unsigned old = xb_add(&bar[XB_XSUB(b.x)], 1u);
;         const unsigned gen = old / nloc;
;         if (old + 1u == (gen + 1u) * nloc) {
.LBB0_31:
	s_or_b64 exec, exec, s[10:11]
	v_cvt_f32_u32_e32 v5, v3
	s_waitcnt vmcnt(0)
	v_readfirstlane_b32 s8, v19
	v_sub_u32_e32 v4, 0, v3
	v_rcp_iflag_f32_e32 v5, v5
	v_add_u32_e32 v6, s8, v2
	v_mul_f32_e32 v5, 0x4f7ffffe, v5
	v_cvt_u32_f32_e32 v5, v5
	v_mul_lo_u32 v2, v4, v5
	v_mul_hi_u32 v2, v5, v2
	v_add_u32_e32 v2, v5, v2
	v_mul_hi_u32 v2, v6, v2
	v_mul_lo_u32 v4, v2, v3
	v_sub_u32_e32 v4, v6, v4
	v_add_u32_e32 v5, 1, v2
	v_cmp_ge_u32_e32 vcc, v4, v3
	s_nop 1
	v_cndmask_b32_e32 v2, v2, v5, vcc
	v_sub_u32_e32 v5, v4, v3
	v_cndmask_b32_e32 v4, v4, v5, vcc
	v_add_u32_e32 v5, 1, v2
	v_cmp_ge_u32_e32 vcc, v4, v3
	v_add_u32_e32 v4, 1, v6
	s_nop 0
	v_cndmask_b32_e32 v2, v2, v5, vcc
	v_mul_lo_u32 v5, v3, v2
	v_add_u32_e32 v3, v5, v3
	v_cmp_ne_u32_e32 vcc, v4, v3
	s_and_saveexec_b64 s[8:9], vcc
	s_xor_b64 s[8:9], exec, s[8:9]
	s_cbranch_execz .LBB0_45
	s_waitcnt lgkmcnt(0)
	buffer_inv sc1
	s_add_u32 s16, s60, 0x7400
	s_addc_u32 s17, s61, 0
	v_add_u32_e32 v2, 1, v2
	v_mul_lo_u32 v2, v2, v1
	s_mov_b64 vcc, 0
	s_and_saveexec_b64 s[10:11], vcc
	s_cbranch_execz .LBB0_44
	s_add_u32 s12, s60, 0x4200
	s_addc_u32 s13, s61, 0
	s_mov_b32 s14, 1
	s_mov_b64 s[18:19], 0
	v_mov_b32_e32 v1, 0
	s_branch .LBB0_35

; __device__ __forceinline__ unsigned xb_add(unsigned* p, unsigned v) { return __hip_atomic_fetch_add(p, v, __ATOMIC_RELAXED, __HIP_MEMORY_SCOPE_AGENT); }
; #define SEAM(k) do { if ((k) < 2) xcd_barrier(bar); else xcd_barrier(barg); } while (0)
; __device__ __forceinline__ void xcd_barrier(const XcdBarrier& b) {
;     ...
;         unsigned nloc = b.st[0], nx = b.st[1];
;         if (nloc == 0u) { xcd_barrier_complete(bar, b.x, b.gsize, nloc, nx); b.st[0] = nloc; b.st[1] = nx; }
;         const unsigned old = xb_add(&bar[XB_XSUB(b.x)], 1u);
; __global__ void __launch_bounds__(NWAVES * 64, 2) fwd(Args a) {
;     ...
;     SEAM(2);
.LBB0_173:
	s_waitcnt vmcnt(0)
	s_ashr_i32 s19, s83, 2
	s_waitcnt vmcnt(0)
	s_barrier
	s_and_saveexec_b64 s[0:1], s[80:81]
	s_xor_b64 s[0:1], exec, s[0:1]
	s_cbranch_execz .LBB0_226
	s_add_i32 s2, 0, 0x26170
	v_mov_b32_e32 v1, s2
	s_waitcnt vmcnt(0) expcnt(0) lgkmcnt(0)
	v_readlane_b32 s4, v250, 13
	s_nop 0
	s_lshl_b32 s4, s4, 8
	s_add_u32 s4, s34, s4
	s_addc_u32 s5, s35, 0
	v_mov_b32_e32 v19, 0x1000
	v_mov_b32_e32 v20, 1
	global_atomic_add v19, v19, v20, s[4:5] offset:1024 sc0
	ds_read_b32 v3, v1
	s_add_i32 s2, 0, 0x26174
	v_mov_b32_e32 v1, s2
	ds_read_b32 v1, v1
	s_waitcnt lgkmcnt(1)
	v_cmp_ne_u32_e32 vcc, 0, v3
	s_cbranch_vccnz .LBB0_189
	s_add_u32 s2, s34, 0x1000
	s_addc_u32 s3, s35, 0
	s_add_u32 s4, s34, 0x1100
	s_addc_u32 s5, s35, 0
	s_add_u32 s6, s34, 0x1200
	s_addc_u32 s7, s35, 0
	s_add_u32 s8, s34, 0x1300
	s_addc_u32 s9, s35, 0
	s_mov_b32 s14, 1
	v_mov_b32_e32 v17, 0
	s_branch .LBB0_177

; __device__ __forceinline__ unsigned xb_ld(unsigned* p)              { return __hip_atomic_load(p, __ATOMIC_RELAXED, __HIP_MEMORY_SCOPE_AGENT); }
; __device__ __forceinline__ unsigned xb_add(unsigned* p, unsigned v) { return __hip_atomic_fetch_add(p, v, __ATOMIC_RELAXED, __HIP_MEMORY_SCOPE_AGENT); }
; #define XB_SPIN(cond, bar) do { unsigned _sp = 0; while (cond) { __builtin_amdgcn_s_sleep(1); \
;     if ((++_sp & 255u) == 0u) { if (xb_ld(&(bar)[XB_TMO])) break; if (_sp > XB_SPIN_CAP) { atomicAdd(&(bar)[XB_TMO], 1u); break; } } } } while (0)
; __device__ __forceinline__ void xcd_barrier(const XcdBarrier& b) {
;     ...
;         const unsigned old = xb_add(&bar[XB_XSUB(b.x)], 1u);
;         const unsigned gen = old / nloc;
;         if (old + 1u == (gen + 1u) * nloc) {
;             __builtin_amdgcn_fence(__ATOMIC_RELEASE, "agent");
;             asm volatile("s_waitcnt vmcnt(0)" ::: "memory");
;             const unsigned og = xb_add(&bar[XB_TOP], 1u);
;             const unsigned tg = og / nx;
;             if (og + 1u == (tg + 1u) * nx) xb_add(&bar[XB_TOPGEN], 1u);
;             else XB_SPIN(xb_ld(&bar[XB_TOPGEN]) == tg, bar);
.LBB0_191:
	s_or_b64 exec, exec, s[6:7]
	v_cvt_f32_u32_e32 v5, v3
	s_waitcnt vmcnt(0)
	v_readfirstlane_b32 s4, v19
	v_sub_u32_e32 v4, 0, v3
	v_rcp_iflag_f32_e32 v5, v5
	v_add_u32_e32 v6, s4, v2
	v_mul_f32_e32 v5, 0x4f7ffffe, v5
	v_cvt_u32_f32_e32 v5, v5
	v_mul_lo_u32 v2, v4, v5
	v_mul_hi_u32 v2, v5, v2
	v_add_u32_e32 v2, v5, v2
	v_mul_hi_u32 v2, v6, v2
	v_mul_lo_u32 v4, v2, v3
	v_sub_u32_e32 v4, v6, v4
	v_add_u32_e32 v5, 1, v2
	v_cmp_ge_u32_e32 vcc, v4, v3
	s_nop 1
	v_cndmask_b32_e32 v2, v2, v5, vcc
	v_sub_u32_e32 v5, v4, v3
	v_cndmask_b32_e32 v4, v4, v5, vcc
	v_add_u32_e32 v5, 1, v2
	v_cmp_ge_u32_e32 vcc, v4, v3
	v_add_u32_e32 v4, 1, v6
	s_nop 0
	v_cndmask_b32_e32 v2, v2, v5, vcc
	v_mul_lo_u32 v5, v3, v2
	v_add_u32_e32 v3, v5, v3
	v_cmp_ne_u32_e32 vcc, v4, v3
	s_and_saveexec_b64 s[4:5], vcc
	s_xor_b64 s[4:5], exec, s[4:5]
	s_cbranch_execz .LBB0_205
	s_waitcnt lgkmcnt(0)
	buffer_inv sc1
	s_add_u32 s8, s34, 0x3400
	s_addc_u32 s9, s35, 0
	v_add_u32_e32 v2, 1, v2
	v_mul_lo_u32 v2, v2, v1
	v_mov_b32_e32 v1, 0
	global_load_dword v1, v1, s[8:9] sc1
	s_waitcnt vmcnt(0)
	v_cmp_lt_u32_e32 vcc, v1, v2
	s_and_saveexec_b64 s[6:7], vcc
	s_cbranch_execz .LBB0_204
	s_mov_b32 s14, 1
	s_mov_b64 s[10:11], 0
	v_mov_b32_e32 v1, 0
	s_branch .LBB0_195
